# LCONV: workgroup->row-block map by XCD (bid%8 selects a contiguous 128-row chunk per pass) so the 3-row conv halo is shared inside one XCD's L2
# speedup vs baseline: 1.0080x; 1.0016x over previous
; __device__ __forceinline__ int opaque_bid() { int t; asm volatile("s_mov_b32 %0, %1" : "=s"(t) : "s"((int)blockIdx.x)); return t; }
; __device__ __forceinline__ void lconv_phase(const bf16_t* REC, bf16_t* XR, const float* cw, const float* cbias, int tid, int G) {
; #pragma unroll 1
;     for (int it = opaque_bid() * 512 + tid; it < MT * 128; it += G * 512) { asm volatile("" : "+v"(it));
;         const int row = it >> 7, ch = (it & 127) * 8;
;         int pos, len; if (row < ML) { pos = row & (SEQ - 1); len = SEQ; } else { pos = (row - ML) & (CTXL - 1); len = CTXL; }
;         float acc[8];
;         { const f32x4 b0 = *(const f32x4*)(cbias + ch), b1 = *(const f32x4*)(cbias + ch + 4);
; #pragma unroll
;           for (int e = 0; e < 4; ++e) { acc[e] = b0[e]; acc[4 + e] = b1[e]; } }
; #pragma unroll
;         for (int k = 0; k < 4; ++k) { const int t = pos + k - 2;
;             if (t >= 0 && t < len) {
;                 const u32x4 v = *(const u32x4*)(REC + (size_t)(row + k - 2) * DM + ch);
;                 const f32x4 w0 = *(const f32x4*)(cw + k * DM + ch), w1 = *(const f32x4*)(cw + k * DM + ch + 4);
.LBB0_70:
	s_and_b64 vcc, exec, s[2:3]
	s_cbranch_vccz .LBB0_83
	v_mov_b32 v0, v220
	s_mov_b32 s2, s54
	s_nop 0
	s_mov_b32 s2, s54
	s_nop 0
	s_and_b32 s3, s2, 7
	s_lshl_b32 s3, s3, 5
	s_lshr_b32 s2, s2, 3
	s_or_b32 s2, s2, s3
	v_lshl_add_u32 v16, s2, 9, v0
	s_mov_b32 s2, 0x440000
	v_cmp_gt_i32_e32 vcc, s2, v16
	s_and_saveexec_b64 s[2:3], vcc
	s_cbranch_execz .LBB0_82
	v_readlane_b32 s6, v254, 41
	v_readlane_b32 s7, v254, 42
	s_load_dwordx2 s[8:9], s[6:7], 0xd8
	s_load_dwordx4 s[16:19], s[6:7], 0x70
	s_ashr_i32 s12, s61, 1
	s_waitcnt lgkmcnt(0)
	s_add_u32 s6, s8, 0xfe00000
	s_addc_u32 s7, s9, 0
	s_add_u32 s8, s8, 0x14200000
	s_addc_u32 s9, s9, 0
	s_ashr_i32 s13, s12, 31
	s_lshl_b64 s[10:11], s[12:13], 14
	s_add_u32 s10, s16, s10
	s_addc_u32 s11, s17, s11
	s_lshl_b64 s[12:13], s[12:13], 12
	s_add_u32 s12, s18, s12
	s_addc_u32 s13, s19, s13
	s_mov_b64 s[16:17], 0
	v_lshlrev_b32_e32 v0, 3, v16
	v_and_b32_e32 v9, 0x3f8, v0
	v_lshlrev_b32_e32 v48, 2, v9
	v_lshlrev_b32_e32 v10, 1, v9
	v_mov_b32_e32 v11, v49
	v_lshl_add_u64 v[12:13], s[10:11], 0, v[48:49]
	v_lshl_add_u64 v[14:15], s[6:7], 0, v[10:11]
	s_mov_b64 s[18:19], 0x1000
	global_load_dwordx4 v[60:63], v48, s[12:13]
	global_load_dwordx4 v[64:67], v48, s[12:13] offset:16
	global_load_dwordx4 v[68:71], v[12:13], off
	global_load_dwordx4 v[72:75], v[12:13], off offset:16
	v_lshl_add_u64 v[20:21], v[12:13], 0, s[18:19]
	s_mov_b64 s[18:19], 0x2000
	global_load_dwordx4 v[76:79], v[20:21], off
	global_load_dwordx4 v[80:83], v[20:21], off offset:16
	v_lshl_add_u64 v[22:23], v[12:13], 0, s[18:19]
	s_mov_b64 s[18:19], 0x3000
	global_load_dwordx4 v[84:87], v[22:23], off
	global_load_dwordx4 v[88:91], v[22:23], off offset:16
	v_lshl_add_u64 v[20:21], v[12:13], 0, s[18:19]
	s_nop 0
	global_load_dwordx4 v[92:95], v[20:21], off
	global_load_dwordx4 v[96:99], v[20:21], off offset:16
	s_waitcnt vmcnt(0)
	s_branch .LBB0_74
